# 64-byte aligned the six GEMM K-loop headers (.p2align 6); no s_setprio; hand-scheduled scan RW loop
# speedup vs baseline: 1.0005x; 1.0005x over previous
.LBB0_439:
	v_lshl_add_u64 v[142:143], v[2:3], 0, s[84:85]
	s_add_u32 s6, s4, 0x100
	v_mov_b32_e32 v2, 0
	s_addc_u32 s7, s5, 0
	s_mov_b32 s4, 0
	v_mov_b32_e32 v3, v2
	v_mov_b32_e32 v4, v2
	v_mov_b32_e32 v5, v2
	v_mov_b32_e32 v6, v2
	v_mov_b32_e32 v7, v2
	v_mov_b32_e32 v8, v2
	v_mov_b32_e32 v9, v2
	v_mov_b32_e32 v10, v2
	v_mov_b32_e32 v11, v2
	v_mov_b32_e32 v12, v2
	v_mov_b32_e32 v13, v2
	v_mov_b32_e32 v18, v2
	v_mov_b32_e32 v19, v2
	v_mov_b32_e32 v20, v2
	v_mov_b32_e32 v21, v2
	v_mov_b32_e32 v26, v2
	v_mov_b32_e32 v27, v2
	v_mov_b32_e32 v28, v2
	v_mov_b32_e32 v29, v2
	v_mov_b32_e32 v34, v2
	v_mov_b32_e32 v35, v2
	v_mov_b32_e32 v36, v2
	v_mov_b32_e32 v37, v2
	v_mov_b32_e32 v42, v2
	v_mov_b32_e32 v43, v2
	v_mov_b32_e32 v44, v2
	v_mov_b32_e32 v45, v2
	v_mov_b32_e32 v50, v2
	v_mov_b32_e32 v51, v2
	v_mov_b32_e32 v52, v2
	v_mov_b32_e32 v53, v2
	v_mov_b32_e32 v14, v2
	v_mov_b32_e32 v15, v2
	v_mov_b32_e32 v16, v2
	v_mov_b32_e32 v17, v2
	v_mov_b32_e32 v22, v2
	v_mov_b32_e32 v23, v2
	v_mov_b32_e32 v24, v2
	v_mov_b32_e32 v25, v2
	v_mov_b32_e32 v30, v2
	v_mov_b32_e32 v31, v2
	v_mov_b32_e32 v32, v2
	v_mov_b32_e32 v33, v2
	v_mov_b32_e32 v38, v2
	v_mov_b32_e32 v39, v2
	v_mov_b32_e32 v40, v2
	v_mov_b32_e32 v41, v2
	v_mov_b32_e32 v46, v2
	v_mov_b32_e32 v47, v2
	v_mov_b32_e32 v48, v2
	v_mov_b32_e32 v49, v2
	v_mov_b32_e32 v54, v2
	v_mov_b32_e32 v55, v2
	v_mov_b32_e32 v56, v2
	v_mov_b32_e32 v57, v2
	v_mov_b32_e32 v58, v2
	v_mov_b32_e32 v59, v2
	v_mov_b32_e32 v60, v2
	v_mov_b32_e32 v61, v2
	v_mov_b32_e32 v62, v2
	v_mov_b32_e32 v63, v2
	v_mov_b32_e32 v64, v2
	v_mov_b32_e32 v65, v2
	v_mov_b32_e32 v66, v2
	v_mov_b32_e32 v67, v2
	v_mov_b32_e32 v68, v2
	v_mov_b32_e32 v69, v2
	v_mov_b32_e32 v70, v2
	v_mov_b32_e32 v71, v2
	v_mov_b32_e32 v72, v2
	v_mov_b32_e32 v73, v2
	v_mov_b32_e32 v74, v2
	v_mov_b32_e32 v75, v2
	v_mov_b32_e32 v76, v2
	v_mov_b32_e32 v77, v2
	v_mov_b32_e32 v82, v2
	v_mov_b32_e32 v83, v2
	v_mov_b32_e32 v84, v2
	v_mov_b32_e32 v85, v2
	v_mov_b32_e32 v90, v2
	v_mov_b32_e32 v91, v2
	v_mov_b32_e32 v92, v2
	v_mov_b32_e32 v93, v2
	v_mov_b32_e32 v98, v2
	v_mov_b32_e32 v99, v2
	v_mov_b32_e32 v100, v2
	v_mov_b32_e32 v101, v2
	v_mov_b32_e32 v106, v2
	v_mov_b32_e32 v107, v2
	v_mov_b32_e32 v108, v2
	v_mov_b32_e32 v109, v2
	v_mov_b32_e32 v114, v2
	v_mov_b32_e32 v115, v2
	v_mov_b32_e32 v116, v2
	v_mov_b32_e32 v117, v2
	v_mov_b32_e32 v78, v2
	v_mov_b32_e32 v79, v2
	v_mov_b32_e32 v80, v2
	v_mov_b32_e32 v81, v2
	v_mov_b32_e32 v86, v2
	v_mov_b32_e32 v87, v2
	v_mov_b32_e32 v88, v2
	v_mov_b32_e32 v89, v2
	v_mov_b32_e32 v94, v2
	v_mov_b32_e32 v95, v2
	v_mov_b32_e32 v96, v2
	v_mov_b32_e32 v97, v2
	v_mov_b32_e32 v102, v2
	v_mov_b32_e32 v103, v2
	v_mov_b32_e32 v104, v2
	v_mov_b32_e32 v105, v2
	v_mov_b32_e32 v110, v2
	v_mov_b32_e32 v111, v2
	v_mov_b32_e32 v112, v2
	v_mov_b32_e32 v113, v2
	v_mov_b32_e32 v118, v2
	v_mov_b32_e32 v119, v2
	v_mov_b32_e32 v120, v2
	v_mov_b32_e32 v121, v2
	v_mov_b32_e32 v122, v2
	v_mov_b32_e32 v123, v2
	v_mov_b32_e32 v124, v2
	v_mov_b32_e32 v125, v2
	v_mov_b32_e32 v126, v2
	v_mov_b32_e32 v127, v2
	v_mov_b32_e32 v128, v2
	v_mov_b32_e32 v129, v2
	.p2align	6

.LBB0_460:
	v_lshl_add_u64 v[148:149], v[2:3], 0, s[84:85]
	s_add_u32 s6, s4, 0x100
	v_mov_b32_e32 v2, 0
	s_addc_u32 s7, s5, 0
	s_mov_b32 s4, 0
	v_mov_b32_e32 v3, v2
	v_mov_b32_e32 v4, v2
	v_mov_b32_e32 v5, v2
	v_mov_b32_e32 v6, v2
	v_mov_b32_e32 v7, v2
	v_mov_b32_e32 v8, v2
	v_mov_b32_e32 v9, v2
	v_mov_b32_e32 v18, v2
	v_mov_b32_e32 v19, v2
	v_mov_b32_e32 v20, v2
	v_mov_b32_e32 v21, v2
	v_mov_b32_e32 v22, v2
	v_mov_b32_e32 v23, v2
	v_mov_b32_e32 v24, v2
	v_mov_b32_e32 v25, v2
	v_mov_b32_e32 v34, v2
	v_mov_b32_e32 v35, v2
	v_mov_b32_e32 v36, v2
	v_mov_b32_e32 v37, v2
	v_mov_b32_e32 v38, v2
	v_mov_b32_e32 v39, v2
	v_mov_b32_e32 v40, v2
	v_mov_b32_e32 v41, v2
	v_mov_b32_e32 v50, v2
	v_mov_b32_e32 v51, v2
	v_mov_b32_e32 v52, v2
	v_mov_b32_e32 v53, v2
	v_mov_b32_e32 v54, v2
	v_mov_b32_e32 v55, v2
	v_mov_b32_e32 v56, v2
	v_mov_b32_e32 v57, v2
	v_mov_b32_e32 v66, v2
	v_mov_b32_e32 v67, v2
	v_mov_b32_e32 v68, v2
	v_mov_b32_e32 v69, v2
	v_mov_b32_e32 v70, v2
	v_mov_b32_e32 v71, v2
	v_mov_b32_e32 v72, v2
	v_mov_b32_e32 v73, v2
	v_mov_b32_e32 v82, v2
	v_mov_b32_e32 v83, v2
	v_mov_b32_e32 v84, v2
	v_mov_b32_e32 v85, v2
	v_mov_b32_e32 v86, v2
	v_mov_b32_e32 v87, v2
	v_mov_b32_e32 v88, v2
	v_mov_b32_e32 v89, v2
	v_mov_b32_e32 v98, v2
	v_mov_b32_e32 v99, v2
	v_mov_b32_e32 v100, v2
	v_mov_b32_e32 v101, v2
	v_mov_b32_e32 v102, v2
	v_mov_b32_e32 v103, v2
	v_mov_b32_e32 v104, v2
	v_mov_b32_e32 v105, v2
	v_mov_b32_e32 v114, v2
	v_mov_b32_e32 v115, v2
	v_mov_b32_e32 v116, v2
	v_mov_b32_e32 v117, v2
	v_mov_b32_e32 v118, v2
	v_mov_b32_e32 v119, v2
	v_mov_b32_e32 v120, v2
	v_mov_b32_e32 v121, v2
	v_mov_b32_e32 v74, v2
	v_mov_b32_e32 v75, v2
	v_mov_b32_e32 v76, v2
	v_mov_b32_e32 v77, v2
	v_mov_b32_e32 v78, v2
	v_mov_b32_e32 v79, v2
	v_mov_b32_e32 v80, v2
	v_mov_b32_e32 v81, v2
	v_mov_b32_e32 v90, v2
	v_mov_b32_e32 v91, v2
	v_mov_b32_e32 v92, v2
	v_mov_b32_e32 v93, v2
	v_mov_b32_e32 v94, v2
	v_mov_b32_e32 v95, v2
	v_mov_b32_e32 v96, v2
	v_mov_b32_e32 v97, v2
	v_mov_b32_e32 v106, v2
	v_mov_b32_e32 v107, v2
	v_mov_b32_e32 v108, v2
	v_mov_b32_e32 v109, v2
	v_mov_b32_e32 v110, v2
	v_mov_b32_e32 v111, v2
	v_mov_b32_e32 v112, v2
	v_mov_b32_e32 v113, v2
	v_mov_b32_e32 v122, v2
	v_mov_b32_e32 v123, v2
	v_mov_b32_e32 v124, v2
	v_mov_b32_e32 v125, v2
	v_mov_b32_e32 v126, v2
	v_mov_b32_e32 v127, v2
	v_mov_b32_e32 v128, v2
	v_mov_b32_e32 v129, v2
	v_mov_b32_e32 v62, v2
	v_mov_b32_e32 v63, v2
	v_mov_b32_e32 v64, v2
	v_mov_b32_e32 v65, v2
	v_mov_b32_e32 v58, v2
	v_mov_b32_e32 v59, v2
	v_mov_b32_e32 v60, v2
	v_mov_b32_e32 v61, v2
	v_mov_b32_e32 v46, v2
	v_mov_b32_e32 v47, v2
	v_mov_b32_e32 v48, v2
	v_mov_b32_e32 v49, v2
	v_mov_b32_e32 v42, v2
	v_mov_b32_e32 v43, v2
	v_mov_b32_e32 v44, v2
	v_mov_b32_e32 v45, v2
	v_mov_b32_e32 v30, v2
	v_mov_b32_e32 v31, v2
	v_mov_b32_e32 v32, v2
	v_mov_b32_e32 v33, v2
	v_mov_b32_e32 v26, v2
	v_mov_b32_e32 v27, v2
	v_mov_b32_e32 v28, v2
	v_mov_b32_e32 v29, v2
	v_mov_b32_e32 v14, v2
	v_mov_b32_e32 v15, v2
	v_mov_b32_e32 v16, v2
	v_mov_b32_e32 v17, v2
	v_mov_b32_e32 v10, v2
	v_mov_b32_e32 v11, v2
	v_mov_b32_e32 v12, v2
	v_mov_b32_e32 v13, v2
	.p2align	6

.LBB0_518:
	s_add_u32 s6, s4, 0x100
	v_mov_b32_e32 v4, 0
	v_lshl_add_u64 v[2:3], v[2:3], 0, s[84:85]
	s_addc_u32 s7, s5, 0
	s_mov_b32 s4, 0
	v_mov_b32_e32 v5, v4
	v_mov_b32_e32 v6, v4
	v_mov_b32_e32 v7, v4
	v_mov_b32_e32 v8, v4
	v_mov_b32_e32 v9, v4
	v_mov_b32_e32 v10, v4
	v_mov_b32_e32 v11, v4
	v_mov_b32_e32 v12, v4
	v_mov_b32_e32 v13, v4
	v_mov_b32_e32 v14, v4
	v_mov_b32_e32 v15, v4
	v_mov_b32_e32 v16, v4
	v_mov_b32_e32 v17, v4
	v_mov_b32_e32 v18, v4
	v_mov_b32_e32 v19, v4
	v_mov_b32_e32 v20, v4
	v_mov_b32_e32 v21, v4
	v_mov_b32_e32 v22, v4
	v_mov_b32_e32 v23, v4
	v_mov_b32_e32 v24, v4
	v_mov_b32_e32 v25, v4
	v_mov_b32_e32 v26, v4
	v_mov_b32_e32 v27, v4
	v_mov_b32_e32 v28, v4
	v_mov_b32_e32 v29, v4
	v_mov_b32_e32 v30, v4
	v_mov_b32_e32 v31, v4
	v_mov_b32_e32 v32, v4
	v_mov_b32_e32 v33, v4
	v_mov_b32_e32 v34, v4
	v_mov_b32_e32 v35, v4
	v_mov_b32_e32 v68, v4
	v_mov_b32_e32 v69, v4
	v_mov_b32_e32 v70, v4
	v_mov_b32_e32 v71, v4
	v_mov_b32_e32 v72, v4
	v_mov_b32_e32 v73, v4
	v_mov_b32_e32 v74, v4
	v_mov_b32_e32 v75, v4
	v_mov_b32_e32 v76, v4
	v_mov_b32_e32 v77, v4
	v_mov_b32_e32 v78, v4
	v_mov_b32_e32 v79, v4
	v_mov_b32_e32 v80, v4
	v_mov_b32_e32 v81, v4
	v_mov_b32_e32 v82, v4
	v_mov_b32_e32 v83, v4
	v_mov_b32_e32 v84, v4
	v_mov_b32_e32 v85, v4
	v_mov_b32_e32 v86, v4
	v_mov_b32_e32 v87, v4
	v_mov_b32_e32 v88, v4
	v_mov_b32_e32 v89, v4
	v_mov_b32_e32 v90, v4
	v_mov_b32_e32 v91, v4
	v_mov_b32_e32 v92, v4
	v_mov_b32_e32 v93, v4
	v_mov_b32_e32 v94, v4
	v_mov_b32_e32 v95, v4
	v_mov_b32_e32 v96, v4
	v_mov_b32_e32 v97, v4
	v_mov_b32_e32 v98, v4
	v_mov_b32_e32 v99, v4
	v_mov_b32_e32 v36, v4
	v_mov_b32_e32 v37, v4
	v_mov_b32_e32 v38, v4
	v_mov_b32_e32 v39, v4
	v_mov_b32_e32 v40, v4
	v_mov_b32_e32 v41, v4
	v_mov_b32_e32 v42, v4
	v_mov_b32_e32 v43, v4
	v_mov_b32_e32 v44, v4
	v_mov_b32_e32 v45, v4
	v_mov_b32_e32 v46, v4
	v_mov_b32_e32 v47, v4
	v_mov_b32_e32 v48, v4
	v_mov_b32_e32 v49, v4
	v_mov_b32_e32 v50, v4
	v_mov_b32_e32 v51, v4
	v_mov_b32_e32 v52, v4
	v_mov_b32_e32 v53, v4
	v_mov_b32_e32 v54, v4
	v_mov_b32_e32 v55, v4
	v_mov_b32_e32 v56, v4
	v_mov_b32_e32 v57, v4
	v_mov_b32_e32 v58, v4
	v_mov_b32_e32 v59, v4
	v_mov_b32_e32 v60, v4
	v_mov_b32_e32 v61, v4
	v_mov_b32_e32 v62, v4
	v_mov_b32_e32 v63, v4
	v_mov_b32_e32 v64, v4
	v_mov_b32_e32 v65, v4
	v_mov_b32_e32 v66, v4
	v_mov_b32_e32 v67, v4
	v_mov_b32_e32 v108, v4
	v_mov_b32_e32 v109, v4
	v_mov_b32_e32 v110, v4
	v_mov_b32_e32 v111, v4
	v_mov_b32_e32 v112, v4
	v_mov_b32_e32 v113, v4
	v_mov_b32_e32 v114, v4
	v_mov_b32_e32 v115, v4
	v_mov_b32_e32 v116, v4
	v_mov_b32_e32 v117, v4
	v_mov_b32_e32 v118, v4
	v_mov_b32_e32 v119, v4
	v_mov_b32_e32 v120, v4
	v_mov_b32_e32 v121, v4
	v_mov_b32_e32 v122, v4
	v_mov_b32_e32 v123, v4
	v_mov_b32_e32 v124, v4
	v_mov_b32_e32 v125, v4
	v_mov_b32_e32 v126, v4
	v_mov_b32_e32 v127, v4
	v_mov_b32_e32 v128, v4
	v_mov_b32_e32 v129, v4
	v_mov_b32_e32 v130, v4
	v_mov_b32_e32 v131, v4
	v_mov_b32_e32 v132, v4
	v_mov_b32_e32 v133, v4
	v_mov_b32_e32 v134, v4
	v_mov_b32_e32 v135, v4
	v_mov_b32_e32 v136, v4
	v_mov_b32_e32 v137, v4
	v_mov_b32_e32 v138, v4
	v_mov_b32_e32 v139, v4
	.p2align	6

.LBB0_648:
	v_lshl_add_u64 v[130:131], v[2:3], 0, s[84:85]
	s_add_u32 s6, s4, 0x100
	v_mov_b32_e32 v2, 0
	s_addc_u32 s7, s5, 0
	s_mov_b32 s4, 0
	v_mov_b32_e32 v3, v2
	v_mov_b32_e32 v4, v2
	v_mov_b32_e32 v5, v2
	v_mov_b32_e32 v6, v2
	s_waitcnt lgkmcnt(0)
	v_mov_b32_e32 v7, v2
	v_mov_b32_e32 v8, v2
	v_mov_b32_e32 v9, v2
	v_mov_b32_e32 v14, v2
	v_mov_b32_e32 v15, v2
	v_mov_b32_e32 v16, v2
	v_mov_b32_e32 v17, v2
	v_mov_b32_e32 v22, v2
	v_mov_b32_e32 v23, v2
	v_mov_b32_e32 v24, v2
	v_mov_b32_e32 v25, v2
	v_mov_b32_e32 v30, v2
	v_mov_b32_e32 v31, v2
	v_mov_b32_e32 v32, v2
	v_mov_b32_e32 v33, v2
	v_mov_b32_e32 v38, v2
	v_mov_b32_e32 v39, v2
	v_mov_b32_e32 v40, v2
	v_mov_b32_e32 v41, v2
	v_mov_b32_e32 v50, v2
	v_mov_b32_e32 v51, v2
	v_mov_b32_e32 v52, v2
	v_mov_b32_e32 v53, v2
	v_mov_b32_e32 v54, v2
	v_mov_b32_e32 v55, v2
	v_mov_b32_e32 v56, v2
	v_mov_b32_e32 v57, v2
	v_mov_b32_e32 v10, v2
	v_mov_b32_e32 v11, v2
	v_mov_b32_e32 v12, v2
	v_mov_b32_e32 v13, v2
	v_mov_b32_e32 v18, v2
	v_mov_b32_e32 v19, v2
	v_mov_b32_e32 v20, v2
	v_mov_b32_e32 v21, v2
	v_mov_b32_e32 v26, v2
	v_mov_b32_e32 v27, v2
	v_mov_b32_e32 v28, v2
	v_mov_b32_e32 v29, v2
	v_mov_b32_e32 v34, v2
	v_mov_b32_e32 v35, v2
	v_mov_b32_e32 v36, v2
	v_mov_b32_e32 v37, v2
	v_mov_b32_e32 v42, v2
	v_mov_b32_e32 v43, v2
	v_mov_b32_e32 v44, v2
	v_mov_b32_e32 v45, v2
	v_mov_b32_e32 v46, v2
	v_mov_b32_e32 v47, v2
	v_mov_b32_e32 v48, v2
	v_mov_b32_e32 v49, v2
	v_mov_b32_e32 v58, v2
	v_mov_b32_e32 v59, v2
	v_mov_b32_e32 v60, v2
	v_mov_b32_e32 v61, v2
	v_mov_b32_e32 v62, v2
	v_mov_b32_e32 v63, v2
	v_mov_b32_e32 v64, v2
	v_mov_b32_e32 v65, v2
	v_mov_b32_e32 v66, v2
	v_mov_b32_e32 v67, v2
	v_mov_b32_e32 v68, v2
	v_mov_b32_e32 v69, v2
	v_mov_b32_e32 v70, v2
	v_mov_b32_e32 v71, v2
	v_mov_b32_e32 v72, v2
	v_mov_b32_e32 v73, v2
	v_mov_b32_e32 v78, v2
	v_mov_b32_e32 v79, v2
	v_mov_b32_e32 v80, v2
	v_mov_b32_e32 v81, v2
	v_mov_b32_e32 v86, v2
	v_mov_b32_e32 v87, v2
	v_mov_b32_e32 v88, v2
	v_mov_b32_e32 v89, v2
	v_mov_b32_e32 v94, v2
	v_mov_b32_e32 v95, v2
	v_mov_b32_e32 v96, v2
	v_mov_b32_e32 v97, v2
	v_mov_b32_e32 v102, v2
	v_mov_b32_e32 v103, v2
	v_mov_b32_e32 v104, v2
	v_mov_b32_e32 v105, v2
	v_mov_b32_e32 v114, v2
	v_mov_b32_e32 v115, v2
	v_mov_b32_e32 v116, v2
	v_mov_b32_e32 v117, v2
	v_mov_b32_e32 v118, v2
	v_mov_b32_e32 v119, v2
	v_mov_b32_e32 v120, v2
	v_mov_b32_e32 v121, v2
	v_mov_b32_e32 v74, v2
	v_mov_b32_e32 v75, v2
	v_mov_b32_e32 v76, v2
	v_mov_b32_e32 v77, v2
	v_mov_b32_e32 v82, v2
	v_mov_b32_e32 v83, v2
	v_mov_b32_e32 v84, v2
	v_mov_b32_e32 v85, v2
	v_mov_b32_e32 v90, v2
	v_mov_b32_e32 v91, v2
	v_mov_b32_e32 v92, v2
	v_mov_b32_e32 v93, v2
	v_mov_b32_e32 v98, v2
	v_mov_b32_e32 v99, v2
	v_mov_b32_e32 v100, v2
	v_mov_b32_e32 v101, v2
	v_mov_b32_e32 v106, v2
	v_mov_b32_e32 v107, v2
	v_mov_b32_e32 v108, v2
	v_mov_b32_e32 v109, v2
	v_mov_b32_e32 v110, v2
	v_mov_b32_e32 v111, v2
	v_mov_b32_e32 v112, v2
	v_mov_b32_e32 v113, v2
	v_mov_b32_e32 v122, v2
	v_mov_b32_e32 v123, v2
	v_mov_b32_e32 v124, v2
	v_mov_b32_e32 v125, v2
	v_mov_b32_e32 v126, v2
	v_mov_b32_e32 v127, v2
	v_mov_b32_e32 v128, v2
	v_mov_b32_e32 v129, v2
	.p2align	6

.LBB0_690:
	s_add_u32 s4, s4, 0x100
	s_waitcnt vmcnt(0)
	v_mov_b32_e32 v66, 0
	v_lshl_add_u64 v[98:99], v[2:3], 0, s[84:85]
	s_addc_u32 s5, s5, 0
	s_mov_b32 s0, 0
	v_mov_b32_e32 v67, v66
	v_mov_b32_e32 v68, v66
	v_mov_b32_e32 v69, v66
	v_mov_b32_e32 v70, v66
	v_mov_b32_e32 v71, v66
	v_mov_b32_e32 v72, v66
	v_mov_b32_e32 v73, v66
	v_mov_b32_e32 v74, v66
	v_mov_b32_e32 v75, v66
	v_mov_b32_e32 v76, v66
	v_mov_b32_e32 v77, v66
	v_mov_b32_e32 v78, v66
	v_mov_b32_e32 v79, v66
	v_mov_b32_e32 v80, v66
	v_mov_b32_e32 v81, v66
	v_mov_b32_e32 v82, v66
	v_mov_b32_e32 v83, v66
	v_mov_b32_e32 v84, v66
	v_mov_b32_e32 v85, v66
	v_mov_b32_e32 v86, v66
	v_mov_b32_e32 v87, v66
	v_mov_b32_e32 v88, v66
	v_mov_b32_e32 v89, v66
	v_mov_b32_e32 v90, v66
	v_mov_b32_e32 v91, v66
	v_mov_b32_e32 v92, v66
	v_mov_b32_e32 v93, v66
	v_mov_b32_e32 v94, v66
	v_mov_b32_e32 v95, v66
	v_mov_b32_e32 v96, v66
	v_mov_b32_e32 v97, v66
	v_mov_b32_e32 v34, v66
	v_mov_b32_e32 v35, v66
	v_mov_b32_e32 v36, v66
	v_mov_b32_e32 v37, v66
	v_mov_b32_e32 v38, v66
	v_mov_b32_e32 v39, v66
	v_mov_b32_e32 v40, v66
	v_mov_b32_e32 v41, v66
	v_mov_b32_e32 v42, v66
	v_mov_b32_e32 v43, v66
	v_mov_b32_e32 v44, v66
	v_mov_b32_e32 v45, v66
	v_mov_b32_e32 v46, v66
	v_mov_b32_e32 v47, v66
	v_mov_b32_e32 v48, v66
	v_mov_b32_e32 v49, v66
	v_mov_b32_e32 v50, v66
	v_mov_b32_e32 v51, v66
	v_mov_b32_e32 v52, v66
	v_mov_b32_e32 v53, v66
	v_mov_b32_e32 v54, v66
	v_mov_b32_e32 v55, v66
	v_mov_b32_e32 v56, v66
	v_mov_b32_e32 v57, v66
	v_mov_b32_e32 v58, v66
	v_mov_b32_e32 v59, v66
	v_mov_b32_e32 v60, v66
	v_mov_b32_e32 v61, v66
	v_mov_b32_e32 v62, v66
	v_mov_b32_e32 v63, v66
	v_mov_b32_e32 v64, v66
	v_mov_b32_e32 v65, v66
	v_mov_b32_e32 v106, v66
	v_mov_b32_e32 v107, v66
	v_mov_b32_e32 v108, v66
	v_mov_b32_e32 v109, v66
	v_mov_b32_e32 v110, v66
	v_mov_b32_e32 v111, v66
	v_mov_b32_e32 v112, v66
	v_mov_b32_e32 v113, v66
	v_mov_b32_e32 v114, v66
	v_mov_b32_e32 v115, v66
	v_mov_b32_e32 v116, v66
	v_mov_b32_e32 v117, v66
	v_mov_b32_e32 v118, v66
	v_mov_b32_e32 v119, v66
	v_mov_b32_e32 v120, v66
	v_mov_b32_e32 v121, v66
	v_mov_b32_e32 v122, v66
	v_mov_b32_e32 v123, v66
	v_mov_b32_e32 v124, v66
	v_mov_b32_e32 v125, v66
	v_mov_b32_e32 v126, v66
	v_mov_b32_e32 v127, v66
	v_mov_b32_e32 v128, v66
	v_mov_b32_e32 v129, v66
	v_mov_b32_e32 v130, v66
	v_mov_b32_e32 v131, v66
	v_mov_b32_e32 v132, v66
	v_mov_b32_e32 v133, v66
	v_mov_b32_e32 v134, v66
	v_mov_b32_e32 v135, v66
	v_mov_b32_e32 v136, v66
	v_mov_b32_e32 v137, v66
	v_mov_b32_e32 v30, v66
	v_mov_b32_e32 v31, v66
	v_mov_b32_e32 v32, v66
	v_mov_b32_e32 v33, v66
	v_mov_b32_e32 v26, v66
	v_mov_b32_e32 v27, v66
	v_mov_b32_e32 v28, v66
	v_mov_b32_e32 v29, v66
	v_mov_b32_e32 v22, v66
	v_mov_b32_e32 v23, v66
	v_mov_b32_e32 v24, v66
	v_mov_b32_e32 v25, v66
	v_mov_b32_e32 v18, v66
	v_mov_b32_e32 v19, v66
	v_mov_b32_e32 v20, v66
	v_mov_b32_e32 v21, v66
	v_mov_b32_e32 v14, v66
	v_mov_b32_e32 v15, v66
	v_mov_b32_e32 v16, v66
	v_mov_b32_e32 v17, v66
	v_mov_b32_e32 v10, v66
	v_mov_b32_e32 v11, v66
	v_mov_b32_e32 v12, v66
	v_mov_b32_e32 v13, v66
	v_mov_b32_e32 v6, v66
	v_mov_b32_e32 v7, v66
	v_mov_b32_e32 v8, v66
	v_mov_b32_e32 v9, v66
	v_mov_b32_e32 v2, v66
	v_mov_b32_e32 v3, v66
	v_mov_b32_e32 v4, v66
	v_mov_b32_e32 v5, v66
	.p2align	6

.LBB0_823:
	v_lshl_add_u64 v[148:149], v[2:3], 0, s[84:85]
	s_add_u32 s4, s4, 0x100
	v_mov_b32_e32 v2, 0
	s_addc_u32 s5, s5, 0
	s_mov_b32 s0, 0
	v_mov_b32_e32 v3, v2
	v_mov_b32_e32 v4, v2
	v_mov_b32_e32 v5, v2
	v_mov_b32_e32 v6, v2
	v_mov_b32_e32 v7, v2
	v_mov_b32_e32 v8, v2
	v_mov_b32_e32 v9, v2
	v_mov_b32_e32 v18, v2
	v_mov_b32_e32 v19, v2
	v_mov_b32_e32 v20, v2
	v_mov_b32_e32 v21, v2
	v_mov_b32_e32 v26, v2
	v_mov_b32_e32 v27, v2
	v_mov_b32_e32 v28, v2
	v_mov_b32_e32 v29, v2
	v_mov_b32_e32 v34, v2
	v_mov_b32_e32 v35, v2
	v_mov_b32_e32 v36, v2
	v_mov_b32_e32 v37, v2
	v_mov_b32_e32 v42, v2
	v_mov_b32_e32 v43, v2
	v_mov_b32_e32 v44, v2
	v_mov_b32_e32 v45, v2
	v_mov_b32_e32 v50, v2
	v_mov_b32_e32 v51, v2
	v_mov_b32_e32 v52, v2
	v_mov_b32_e32 v53, v2
	v_mov_b32_e32 v58, v2
	v_mov_b32_e32 v59, v2
	v_mov_b32_e32 v60, v2
	v_mov_b32_e32 v61, v2
	v_mov_b32_e32 v66, v2
	v_mov_b32_e32 v67, v2
	v_mov_b32_e32 v68, v2
	v_mov_b32_e32 v69, v2
	v_mov_b32_e32 v74, v2
	v_mov_b32_e32 v75, v2
	v_mov_b32_e32 v76, v2
	v_mov_b32_e32 v77, v2
	v_mov_b32_e32 v82, v2
	v_mov_b32_e32 v83, v2
	v_mov_b32_e32 v84, v2
	v_mov_b32_e32 v85, v2
	v_mov_b32_e32 v90, v2
	v_mov_b32_e32 v91, v2
	v_mov_b32_e32 v92, v2
	v_mov_b32_e32 v93, v2
	v_mov_b32_e32 v98, v2
	v_mov_b32_e32 v99, v2
	v_mov_b32_e32 v100, v2
	v_mov_b32_e32 v101, v2
	v_mov_b32_e32 v106, v2
	v_mov_b32_e32 v107, v2
	v_mov_b32_e32 v108, v2
	v_mov_b32_e32 v109, v2
	v_mov_b32_e32 v114, v2
	v_mov_b32_e32 v115, v2
	v_mov_b32_e32 v116, v2
	v_mov_b32_e32 v117, v2
	v_mov_b32_e32 v122, v2
	v_mov_b32_e32 v123, v2
	v_mov_b32_e32 v124, v2
	v_mov_b32_e32 v125, v2
	v_mov_b32_e32 v70, v2
	v_mov_b32_e32 v71, v2
	v_mov_b32_e32 v72, v2
	v_mov_b32_e32 v73, v2
	v_mov_b32_e32 v78, v2
	v_mov_b32_e32 v79, v2
	v_mov_b32_e32 v80, v2
	v_mov_b32_e32 v81, v2
	v_mov_b32_e32 v86, v2
	v_mov_b32_e32 v87, v2
	v_mov_b32_e32 v88, v2
	v_mov_b32_e32 v89, v2
	v_mov_b32_e32 v94, v2
	v_mov_b32_e32 v95, v2
	v_mov_b32_e32 v96, v2
	v_mov_b32_e32 v97, v2
	v_mov_b32_e32 v102, v2
	v_mov_b32_e32 v103, v2
	v_mov_b32_e32 v104, v2
	v_mov_b32_e32 v105, v2
	v_mov_b32_e32 v110, v2
	v_mov_b32_e32 v111, v2
	v_mov_b32_e32 v112, v2
	v_mov_b32_e32 v113, v2
	v_mov_b32_e32 v118, v2
	v_mov_b32_e32 v119, v2
	v_mov_b32_e32 v120, v2
	v_mov_b32_e32 v121, v2
	v_mov_b32_e32 v126, v2
	v_mov_b32_e32 v127, v2
	v_mov_b32_e32 v128, v2
	v_mov_b32_e32 v129, v2
	v_mov_b32_e32 v62, v2
	v_mov_b32_e32 v63, v2
	v_mov_b32_e32 v64, v2
	v_mov_b32_e32 v65, v2
	v_mov_b32_e32 v54, v2
	v_mov_b32_e32 v55, v2
	v_mov_b32_e32 v56, v2
	v_mov_b32_e32 v57, v2
	v_mov_b32_e32 v46, v2
	v_mov_b32_e32 v47, v2
	v_mov_b32_e32 v48, v2
	v_mov_b32_e32 v49, v2
	v_mov_b32_e32 v38, v2
	v_mov_b32_e32 v39, v2
	v_mov_b32_e32 v40, v2
	v_mov_b32_e32 v41, v2
	v_mov_b32_e32 v30, v2
	v_mov_b32_e32 v31, v2
	v_mov_b32_e32 v32, v2
	v_mov_b32_e32 v33, v2
	v_mov_b32_e32 v22, v2
	v_mov_b32_e32 v23, v2
	v_mov_b32_e32 v24, v2
	v_mov_b32_e32 v25, v2
	v_mov_b32_e32 v14, v2
	v_mov_b32_e32 v15, v2
	v_mov_b32_e32 v16, v2
	v_mov_b32_e32 v17, v2
	v_mov_b32_e32 v10, v2
	v_mov_b32_e32 v11, v2
	v_mov_b32_e32 v12, v2
	v_mov_b32_e32 v13, v2
	.p2align	6
